# RMSNorm loops: the 7 intermediate row stores deferred (packed results parked in fresh VGPRs), all 8 stores issued at row end so per-group vmcnt waits no longer include a store ack (on top of v18)
# baseline (speedup 1.0000x reference)
.LBB0_58:
	s_or_b64 exec, exec, s[4:5]
	v_lshl_add_u64 v[0:1], v[0:1], 0, v[30:31]
	global_load_dwordx4 v[74:77], v[0:1], off
	global_load_dwordx4 v[24:27], v[0:1], off offset:1024
	global_load_dwordx4 v[20:23], v[0:1], off offset:2048
	global_load_dwordx4 v[16:19], v[0:1], off offset:3072
	v_add_co_u32_e64 v62, s[4:5], s3, v0
	v_lshrrev_b32_e32 v47, 10, v60
	s_nop 0
	v_addc_co_u32_e64 v63, s[4:5], 0, v1, s[4:5]
	global_load_dwordx4 v[12:15], v[62:63], off
	global_load_dwordx4 v[8:11], v[62:63], off offset:1024
	global_load_dwordx4 v[4:7], v[62:63], off offset:2048
	global_load_dwordx4 v[0:3], v[62:63], off offset:3072
	v_add_u32_e32 v47, 1, v47
	v_mov_b64_e32 v[60:61], s[20:21]
	v_cndmask_b32_e64 v47, v47, 0, vcc
	v_mad_u64_u32 v[60:61], s[0:1], v47, s23, v[60:61]
	v_lshl_add_u64 v[62:63], v[60:61], 0, s[18:19]
	global_load_dwordx4 v[78:81], v[32:33], off
	v_lshl_add_u64 v[92:93], v[62:63], 0, v[30:31]
	v_lshl_add_u64 v[90:91], v[60:61], 0, v[30:31]
	global_load_dwordx4 v[82:85], v[92:93], off
	global_load_dwordx4 v[86:89], v[90:91], off
	v_lshlrev_b64 v[64:65], 12, v[64:65]
	v_lshl_add_u64 v[64:65], v[42:43], 0, v[64:65]
	v_mov_b32_e32 v55, v31
	v_mov_b32_e32 v57, v31
	v_mov_b32_e32 v59, v31
	v_lshl_add_u64 v[28:29], v[28:29], 0, s[12:13]
	v_lshl_add_u64 v[44:45], v[44:45], 0, s[14:15]
	s_waitcnt vmcnt(10)
	v_mul_f32_e32 v47, v75, v75
	s_waitcnt vmcnt(9)
	v_mul_f32_e32 v49, v25, v25
	s_waitcnt vmcnt(8)
	v_mul_f32_e32 v51, v21, v21
	v_fmac_f32_e32 v47, v74, v74
	v_fmac_f32_e32 v49, v24, v24
	s_waitcnt vmcnt(7)
	v_mul_f32_e32 v53, v17, v17
	v_fmac_f32_e32 v51, v20, v20
	s_waitcnt vmcnt(6)
	v_mov_b32_e32 v94, v13
	s_waitcnt vmcnt(5)
	v_mov_b32_e32 v95, v9
	v_fmac_f32_e32 v47, v76, v76
	v_fmac_f32_e32 v49, v26, v26
	v_fmac_f32_e32 v53, v16, v16
	v_mov_b32_e32 v92, v12
	v_mov_b32_e32 v93, v8
	v_fmac_f32_e32 v51, v22, v22
	v_pk_mul_f32 v[94:95], v[94:95], v[94:95]
	v_fmac_f32_e32 v47, v77, v77
	v_fmac_f32_e32 v49, v27, v27
	v_mov_b32_e32 v96, v14
	v_mov_b32_e32 v97, v10
	s_waitcnt vmcnt(4)
	v_mov_b32_e32 v102, v5
	s_waitcnt vmcnt(3)
	v_mov_b32_e32 v103, v1
	v_fmac_f32_e32 v53, v18, v18
	v_fmac_f32_e32 v51, v23, v23
	v_pk_fma_f32 v[92:93], v[92:93], v[92:93], v[94:95]
	v_add_f32_e32 v47, v47, v49
	v_mov_b32_e32 v98, v15
	v_mov_b32_e32 v99, v11
	v_mov_b32_e32 v100, v4
	v_mov_b32_e32 v101, v0
	v_pk_mul_f32 v[102:103], v[102:103], v[102:103]
	v_fmac_f32_e32 v53, v19, v19
	v_pk_fma_f32 v[92:93], v[96:97], v[96:97], v[92:93]
	v_add_f32_e32 v47, v47, v51
	v_mov_b32_e32 v104, v6
	v_mov_b32_e32 v105, v2
	v_pk_fma_f32 v[94:95], v[100:101], v[100:101], v[102:103]
	v_pk_fma_f32 v[92:93], v[98:99], v[98:99], v[92:93]
	v_add_f32_e32 v47, v47, v53
	v_mov_b32_e32 v106, v7
	v_mov_b32_e32 v107, v3
	v_pk_fma_f32 v[94:95], v[104:105], v[104:105], v[94:95]
	v_add_f32_e32 v47, v47, v92
	v_pk_fma_f32 v[94:95], v[106:107], v[106:107], v[94:95]
	v_add_f32_e32 v47, v47, v93
	v_add_f32_e32 v47, v47, v94
	v_add_f32_e32 v47, v47, v95
	ds_bpermute_b32 v49, v67, v47
	s_waitcnt vmcnt(1)
	v_pk_add_f32 v[82:83], v[82:83], 1.0 op_sel_hi:[1,0]
	v_pk_add_f32 v[84:85], v[84:85], 1.0 op_sel_hi:[1,0]
	v_mov_b32_e32 v53, v31
	s_waitcnt lgkmcnt(0)
	v_add_f32_e32 v47, v47, v49
	ds_bpermute_b32 v49, v68, v47
	s_waitcnt lgkmcnt(0)
	v_add_f32_e32 v47, v47, v49
	ds_bpermute_b32 v49, v69, v47
	s_waitcnt lgkmcnt(0)
	v_add_f32_e32 v47, v47, v49
	ds_bpermute_b32 v49, v70, v47
	s_waitcnt lgkmcnt(0)
	v_add_f32_e32 v47, v47, v49
	ds_bpermute_b32 v49, v71, v47
	s_waitcnt lgkmcnt(0)
	v_add_f32_e32 v49, v47, v49
	ds_bpermute_b32 v51, v72, v49
	v_mov_b32_e32 v47, v31
	s_waitcnt lgkmcnt(0)
	v_add_f32_e32 v49, v49, v51
	v_fmamk_f32 v49, v49, 0x3a000000, v73
	v_mul_f32_e32 v51, 0x4b800000, v49
	v_cmp_gt_f32_e32 vcc, s24, v49
	s_nop 1
	v_cndmask_b32_e32 v49, v49, v51, vcc
	v_rsq_f32_e32 v49, v49
	s_nop 0
	v_mul_f32_e32 v51, 0x45800000, v49
	v_cndmask_b32_e32 v66, v49, v51, vcc
	v_pk_mul_f32 v[74:75], v[74:75], v[66:67] op_sel_hi:[1,0]
	v_pk_mul_f32 v[76:77], v[76:77], v[66:67] op_sel_hi:[1,0]
	v_pk_mul_f32 v[74:75], v[78:79], v[74:75]
	v_pk_mul_f32 v[76:77], v[80:81], v[76:77]
	s_waitcnt vmcnt(0)
	v_pk_fma_f32 v[74:75], v[82:83], v[74:75], v[86:87]
	v_pk_fma_f32 v[76:77], v[84:85], v[76:77], v[88:89]
	v_cvt_pk_bf16_f32 v74, v74, v75
	v_lshl_add_u64 v[86:87], v[62:63], 0, v[46:47]
	v_cvt_pk_bf16_f32 v75, v76, v77
	v_mov_b32_e32 v120, v74
	v_mov_b32_e32 v121, v75
	global_load_dwordx4 v[74:77], v[32:33], off offset:1024
	s_nop 0
	global_load_dwordx4 v[78:81], v[86:87], off
	global_load_dwordx4 v[82:85], v[90:91], off offset:1024
	v_pk_mul_f32 v[26:27], v[26:27], v[66:67] op_sel_hi:[1,0]
	v_pk_mul_f32 v[24:25], v[24:25], v[66:67] op_sel_hi:[1,0]
	v_mov_b32_e32 v49, v31
	v_pk_mul_f32 v[22:23], v[22:23], v[66:67] op_sel_hi:[1,0]
	v_pk_mul_f32 v[20:21], v[20:21], v[66:67] op_sel_hi:[1,0]
	v_mov_b32_e32 v51, v31
	v_pk_mul_f32 v[18:19], v[18:19], v[66:67] op_sel_hi:[1,0]
	v_pk_mul_f32 v[16:17], v[16:17], v[66:67] op_sel_hi:[1,0]
	v_pk_mul_f32 v[14:15], v[14:15], v[66:67] op_sel_hi:[1,0]
	v_pk_mul_f32 v[12:13], v[12:13], v[66:67] op_sel_hi:[1,0]
	v_pk_mul_f32 v[10:11], v[10:11], v[66:67] op_sel_hi:[1,0]
	v_pk_mul_f32 v[8:9], v[8:9], v[66:67] op_sel_hi:[1,0]
	v_pk_mul_f32 v[6:7], v[6:7], v[66:67] op_sel_hi:[1,0]
	v_pk_mul_f32 v[4:5], v[4:5], v[66:67] op_sel_hi:[1,0]
	v_pk_mul_f32 v[2:3], v[2:3], v[66:67] op_sel_hi:[1,0]
	v_pk_mul_f32 v[0:1], v[0:1], v[66:67] op_sel_hi:[1,0]
	v_cmp_lt_i32_e32 vcc, s25, v28
	s_or_b64 s[16:17], vcc, s[16:17]
	s_waitcnt vmcnt(2)
	v_pk_mul_f32 v[24:25], v[74:75], v[24:25]
	v_pk_mul_f32 v[26:27], v[76:77], v[26:27]
	s_waitcnt vmcnt(1)
	v_pk_add_f32 v[76:77], v[78:79], 1.0 op_sel_hi:[1,0]
	v_pk_add_f32 v[74:75], v[80:81], 1.0 op_sel_hi:[1,0]
	s_waitcnt vmcnt(0)
	v_pk_fma_f32 v[24:25], v[76:77], v[24:25], v[82:83]
	v_pk_fma_f32 v[26:27], v[74:75], v[26:27], v[84:85]
	v_cvt_pk_bf16_f32 v24, v24, v25
	v_lshl_add_u64 v[82:83], v[62:63], 0, v[48:49]
	v_cvt_pk_bf16_f32 v25, v26, v27
	v_mov_b32_e32 v122, v24
	v_mov_b32_e32 v123, v25
	global_load_dwordx4 v[24:27], v[32:33], off offset:2048
	s_nop 0
	global_load_dwordx4 v[74:77], v[82:83], off
	global_load_dwordx4 v[78:81], v[90:91], off offset:2048
	s_waitcnt vmcnt(2)
	v_pk_mul_f32 v[20:21], v[24:25], v[20:21]
	v_pk_mul_f32 v[22:23], v[26:27], v[22:23]
	s_waitcnt vmcnt(1)
	v_pk_add_f32 v[26:27], v[74:75], 1.0 op_sel_hi:[1,0]
	v_pk_add_f32 v[24:25], v[76:77], 1.0 op_sel_hi:[1,0]
	s_waitcnt vmcnt(0)
	v_pk_fma_f32 v[20:21], v[26:27], v[20:21], v[78:79]
	v_pk_fma_f32 v[22:23], v[24:25], v[22:23], v[80:81]
	v_cvt_pk_bf16_f32 v20, v20, v21
	v_lshl_add_u64 v[78:79], v[62:63], 0, v[50:51]
	v_cvt_pk_bf16_f32 v21, v22, v23
	v_mov_b32_e32 v124, v20
	v_mov_b32_e32 v125, v21
	global_load_dwordx4 v[20:23], v[32:33], off offset:3072
	s_nop 0
	global_load_dwordx4 v[24:27], v[78:79], off
	global_load_dwordx4 v[74:77], v[90:91], off offset:3072
	s_waitcnt vmcnt(2)
	v_pk_mul_f32 v[16:17], v[16:17], v[20:21]
	v_pk_mul_f32 v[18:19], v[18:19], v[22:23]
	s_waitcnt vmcnt(1)
	v_pk_add_f32 v[22:23], v[24:25], 1.0 op_sel_hi:[1,0]
	v_pk_add_f32 v[20:21], v[26:27], 1.0 op_sel_hi:[1,0]
	s_waitcnt vmcnt(0)
	v_pk_fma_f32 v[16:17], v[16:17], v[22:23], v[74:75]
	v_pk_fma_f32 v[18:19], v[18:19], v[20:21], v[76:77]
	v_cvt_pk_bf16_f32 v16, v16, v17
	v_lshl_add_u64 v[20:21], v[62:63], 0, v[52:53]
	v_cvt_pk_bf16_f32 v17, v18, v19
	v_mov_b32_e32 v126, v16
	v_mov_b32_e32 v127, v17
	global_load_dwordx4 v[16:19], v[34:35], off
	v_lshl_add_u64 v[24:25], v[60:61], 0, v[52:53]
	global_load_dwordx4 v[20:23], v[20:21], off
	s_waitcnt vmcnt(1)
	v_pk_mul_f32 v[12:13], v[12:13], v[16:17]
	global_load_dwordx4 v[24:27], v[24:25], off
	v_pk_mul_f32 v[14:15], v[14:15], v[18:19]
	s_waitcnt vmcnt(1)
	v_pk_add_f32 v[18:19], v[20:21], 1.0 op_sel_hi:[1,0]
	v_pk_add_f32 v[16:17], v[22:23], 1.0 op_sel_hi:[1,0]
	v_lshl_add_u64 v[20:21], v[60:61], 0, v[54:55]
	s_waitcnt vmcnt(0)
	v_pk_fma_f32 v[12:13], v[12:13], v[18:19], v[24:25]
	v_pk_fma_f32 v[14:15], v[14:15], v[16:17], v[26:27]
	v_cvt_pk_bf16_f32 v12, v12, v13
	v_lshl_add_u64 v[16:17], v[62:63], 0, v[54:55]
	v_cvt_pk_bf16_f32 v13, v14, v15
	v_mov_b32_e32 v128, v12
	v_mov_b32_e32 v129, v13
	global_load_dwordx4 v[12:15], v[36:37], off
	s_waitcnt vmcnt(0)
	v_pk_mul_f32 v[8:9], v[8:9], v[12:13]
	global_load_dwordx4 v[16:19], v[16:17], off
	v_pk_mul_f32 v[10:11], v[10:11], v[14:15]
	global_load_dwordx4 v[20:23], v[20:21], off
	s_waitcnt vmcnt(1)
	v_pk_add_f32 v[14:15], v[16:17], 1.0 op_sel_hi:[1,0]
	v_pk_add_f32 v[12:13], v[18:19], 1.0 op_sel_hi:[1,0]
	s_waitcnt vmcnt(0)
	v_pk_fma_f32 v[8:9], v[8:9], v[14:15], v[20:21]
	v_pk_fma_f32 v[10:11], v[10:11], v[12:13], v[22:23]
	v_cvt_pk_bf16_f32 v8, v8, v9
	v_lshl_add_u64 v[12:13], v[62:63], 0, v[56:57]
	v_cvt_pk_bf16_f32 v9, v10, v11
	v_mov_b32_e32 v130, v8
	v_mov_b32_e32 v131, v9
	global_load_dwordx4 v[8:11], v[38:39], off
	v_lshl_add_u64 v[16:17], v[60:61], 0, v[56:57]
	global_load_dwordx4 v[12:15], v[12:13], off
	s_waitcnt vmcnt(1)
	v_pk_mul_f32 v[4:5], v[4:5], v[8:9]
	global_load_dwordx4 v[16:19], v[16:17], off
	v_pk_mul_f32 v[6:7], v[6:7], v[10:11]
	s_waitcnt vmcnt(1)
	v_pk_add_f32 v[10:11], v[12:13], 1.0 op_sel_hi:[1,0]
	v_pk_add_f32 v[8:9], v[14:15], 1.0 op_sel_hi:[1,0]
	v_lshl_add_u64 v[12:13], v[60:61], 0, v[58:59]
	s_waitcnt vmcnt(0)
	v_pk_fma_f32 v[4:5], v[4:5], v[10:11], v[16:17]
	v_pk_fma_f32 v[6:7], v[6:7], v[8:9], v[18:19]
	v_cvt_pk_bf16_f32 v4, v4, v5
	v_lshl_add_u64 v[8:9], v[62:63], 0, v[58:59]
	v_cvt_pk_bf16_f32 v5, v6, v7
	v_mov_b32_e32 v132, v4
	v_mov_b32_e32 v133, v5
	global_load_dwordx4 v[4:7], v[40:41], off
	s_waitcnt vmcnt(0)
	v_pk_mul_f32 v[0:1], v[0:1], v[4:5]
	global_load_dwordx4 v[8:11], v[8:9], off
	v_pk_mul_f32 v[2:3], v[2:3], v[6:7]
	global_load_dwordx4 v[12:15], v[12:13], off
	s_waitcnt vmcnt(1)
	v_pk_add_f32 v[6:7], v[8:9], 1.0 op_sel_hi:[1,0]
	v_pk_add_f32 v[4:5], v[10:11], 1.0 op_sel_hi:[1,0]
	s_waitcnt vmcnt(0)
	v_pk_fma_f32 v[0:1], v[0:1], v[6:7], v[12:13]
	v_pk_fma_f32 v[2:3], v[2:3], v[4:5], v[14:15]
	v_cvt_pk_bf16_f32 v0, v0, v1
	s_nop 0
	v_cvt_pk_bf16_f32 v1, v2, v3
	global_store_dwordx2 v[64:65], v[120:121], off
	global_store_dwordx2 v[64:65], v[122:123], off offset:512
	global_store_dwordx2 v[64:65], v[124:125], off offset:1024
	global_store_dwordx2 v[64:65], v[126:127], off offset:1536
	global_store_dwordx2 v[64:65], v[128:129], off offset:2048
	global_store_dwordx2 v[64:65], v[130:131], off offset:2560
	global_store_dwordx2 v[64:65], v[132:133], off offset:3072
	global_store_dwordx2 v[64:65], v[0:1], off offset:3584
	s_andn2_b64 exec, exec, s[16:17]
	s_cbranch_execz .LBB0_63

.LBB0_363:
	s_or_b64 exec, exec, s[4:5]
	v_lshl_add_u64 v[0:1], v[0:1], 0, v[30:31]
	global_load_dwordx4 v[74:77], v[0:1], off
	global_load_dwordx4 v[24:27], v[0:1], off offset:1024
	global_load_dwordx4 v[20:23], v[0:1], off offset:2048
	global_load_dwordx4 v[16:19], v[0:1], off offset:3072
	v_add_co_u32_e64 v62, s[4:5], s24, v0
	v_lshrrev_b32_e32 v47, 10, v60
	s_nop 0
	v_addc_co_u32_e64 v63, s[4:5], 0, v1, s[4:5]
	global_load_dwordx4 v[12:15], v[62:63], off
	global_load_dwordx4 v[8:11], v[62:63], off offset:1024
	global_load_dwordx4 v[4:7], v[62:63], off offset:2048
	global_load_dwordx4 v[0:3], v[62:63], off offset:3072
	v_add_u32_e32 v47, 1, v47
	v_mov_b64_e32 v[60:61], s[20:21]
	v_cndmask_b32_e64 v47, v47, 0, vcc
	v_mad_u64_u32 v[62:63], s[0:1], v47, s26, v[60:61]
	v_lshl_add_u64 v[60:61], v[62:63], 0, s[18:19]
	v_lshl_add_u64 v[62:63], v[62:63], 0, s[22:23]
	global_load_dwordx4 v[78:81], v[32:33], off
	v_lshl_add_u64 v[90:91], v[62:63], 0, v[30:31]
	v_lshl_add_u64 v[92:93], v[60:61], 0, v[30:31]
	global_load_dwordx4 v[82:85], v[90:91], off
	global_load_dwordx4 v[86:89], v[92:93], off
	v_lshlrev_b64 v[64:65], 12, v[64:65]
	v_lshl_add_u64 v[64:65], v[42:43], 0, v[64:65]
	v_mov_b32_e32 v55, v31
	v_mov_b32_e32 v57, v31
	v_mov_b32_e32 v59, v31
	v_lshl_add_u64 v[28:29], v[28:29], 0, s[12:13]
	v_lshl_add_u64 v[44:45], v[44:45], 0, s[14:15]
	s_waitcnt vmcnt(10)
	v_mul_f32_e32 v47, v75, v75
	s_waitcnt vmcnt(9)
	v_mul_f32_e32 v49, v25, v25
	s_waitcnt vmcnt(8)
	v_mul_f32_e32 v51, v21, v21
	v_fmac_f32_e32 v47, v74, v74
	v_fmac_f32_e32 v49, v24, v24
	s_waitcnt vmcnt(7)
	v_mul_f32_e32 v53, v17, v17
	v_fmac_f32_e32 v51, v20, v20
	s_waitcnt vmcnt(6)
	v_mov_b32_e32 v92, v13
	s_waitcnt vmcnt(5)
	v_mov_b32_e32 v93, v9
	v_fmac_f32_e32 v47, v76, v76
	v_fmac_f32_e32 v49, v26, v26
	v_fmac_f32_e32 v53, v16, v16
	v_mov_b32_e32 v90, v12
	v_mov_b32_e32 v91, v8
	v_fmac_f32_e32 v51, v22, v22
	v_pk_mul_f32 v[92:93], v[92:93], v[92:93]
	v_fmac_f32_e32 v47, v77, v77
	v_fmac_f32_e32 v49, v27, v27
	v_mov_b32_e32 v94, v14
	v_mov_b32_e32 v95, v10
	s_waitcnt vmcnt(4)
	v_mov_b32_e32 v100, v5
	s_waitcnt vmcnt(3)
	v_mov_b32_e32 v101, v1
	v_fmac_f32_e32 v53, v18, v18
	v_fmac_f32_e32 v51, v23, v23
	v_pk_fma_f32 v[90:91], v[90:91], v[90:91], v[92:93]
	v_add_f32_e32 v47, v47, v49
	v_mov_b32_e32 v96, v15
	v_mov_b32_e32 v97, v11
	v_mov_b32_e32 v98, v4
	v_mov_b32_e32 v99, v0
	v_pk_mul_f32 v[100:101], v[100:101], v[100:101]
	v_fmac_f32_e32 v53, v19, v19
	v_pk_fma_f32 v[90:91], v[94:95], v[94:95], v[90:91]
	v_add_f32_e32 v47, v47, v51
	v_mov_b32_e32 v102, v6
	v_mov_b32_e32 v103, v2
	v_pk_fma_f32 v[92:93], v[98:99], v[98:99], v[100:101]
	v_pk_fma_f32 v[90:91], v[96:97], v[96:97], v[90:91]
	v_add_f32_e32 v47, v47, v53
	v_mov_b32_e32 v104, v7
	v_mov_b32_e32 v105, v3
	v_pk_fma_f32 v[92:93], v[102:103], v[102:103], v[92:93]
	v_add_f32_e32 v47, v47, v90
	v_pk_fma_f32 v[92:93], v[104:105], v[104:105], v[92:93]
	v_add_f32_e32 v47, v47, v91
	v_add_f32_e32 v47, v47, v92
	v_add_f32_e32 v47, v47, v93
	ds_bpermute_b32 v49, v67, v47
	s_waitcnt vmcnt(1)
	v_pk_add_f32 v[82:83], v[82:83], 1.0 op_sel_hi:[1,0]
	v_pk_add_f32 v[84:85], v[84:85], 1.0 op_sel_hi:[1,0]
	v_mov_b32_e32 v53, v31
	s_waitcnt lgkmcnt(0)
	v_add_f32_e32 v47, v47, v49
	ds_bpermute_b32 v49, v68, v47
	s_waitcnt lgkmcnt(0)
	v_add_f32_e32 v47, v47, v49
	ds_bpermute_b32 v49, v69, v47
	s_waitcnt lgkmcnt(0)
	v_add_f32_e32 v47, v47, v49
	ds_bpermute_b32 v49, v70, v47
	s_waitcnt lgkmcnt(0)
	v_add_f32_e32 v47, v47, v49
	ds_bpermute_b32 v49, v71, v47
	s_waitcnt lgkmcnt(0)
	v_add_f32_e32 v49, v47, v49
	ds_bpermute_b32 v51, v72, v49
	v_mov_b32_e32 v47, v31
	s_waitcnt lgkmcnt(0)
	v_add_f32_e32 v49, v49, v51
	v_fmamk_f32 v49, v49, 0x3a000000, v73
	v_mul_f32_e32 v51, 0x4b800000, v49
	v_cmp_gt_f32_e32 vcc, s27, v49
	s_nop 1
	v_cndmask_b32_e32 v49, v49, v51, vcc
	v_rsq_f32_e32 v49, v49
	s_nop 0
	v_mul_f32_e32 v51, 0x45800000, v49
	v_cndmask_b32_e32 v66, v49, v51, vcc
	v_pk_mul_f32 v[74:75], v[74:75], v[66:67] op_sel_hi:[1,0]
	v_pk_mul_f32 v[76:77], v[76:77], v[66:67] op_sel_hi:[1,0]
	v_pk_mul_f32 v[74:75], v[78:79], v[74:75]
	v_pk_mul_f32 v[76:77], v[80:81], v[76:77]
	s_waitcnt vmcnt(0)
	v_pk_fma_f32 v[74:75], v[82:83], v[74:75], v[86:87]
	v_pk_fma_f32 v[76:77], v[84:85], v[76:77], v[88:89]
	v_cvt_pk_bf16_f32 v74, v74, v75
	v_lshl_add_u64 v[78:79], v[62:63], 0, v[46:47]
	v_cvt_pk_bf16_f32 v75, v76, v77
	v_mov_b32_e32 v120, v74
	v_mov_b32_e32 v121, v75
	global_load_dwordx4 v[74:77], v[32:33], off offset:1024
	v_lshl_add_u64 v[82:83], v[60:61], 0, v[46:47]
	global_load_dwordx4 v[78:81], v[78:79], off
	v_pk_mul_f32 v[26:27], v[26:27], v[66:67] op_sel_hi:[1,0]
	global_load_dwordx4 v[82:85], v[82:83], off
	v_pk_mul_f32 v[24:25], v[24:25], v[66:67] op_sel_hi:[1,0]
	v_mov_b32_e32 v49, v31
	v_pk_mul_f32 v[22:23], v[22:23], v[66:67] op_sel_hi:[1,0]
	v_pk_mul_f32 v[20:21], v[20:21], v[66:67] op_sel_hi:[1,0]
	v_mov_b32_e32 v51, v31
	v_pk_mul_f32 v[18:19], v[18:19], v[66:67] op_sel_hi:[1,0]
	v_pk_mul_f32 v[16:17], v[16:17], v[66:67] op_sel_hi:[1,0]
	v_pk_mul_f32 v[14:15], v[14:15], v[66:67] op_sel_hi:[1,0]
	v_pk_mul_f32 v[12:13], v[12:13], v[66:67] op_sel_hi:[1,0]
	v_pk_mul_f32 v[10:11], v[10:11], v[66:67] op_sel_hi:[1,0]
	v_pk_mul_f32 v[8:9], v[8:9], v[66:67] op_sel_hi:[1,0]
	v_pk_mul_f32 v[6:7], v[6:7], v[66:67] op_sel_hi:[1,0]
	v_pk_mul_f32 v[4:5], v[4:5], v[66:67] op_sel_hi:[1,0]
	v_pk_mul_f32 v[2:3], v[2:3], v[66:67] op_sel_hi:[1,0]
	v_pk_mul_f32 v[0:1], v[0:1], v[66:67] op_sel_hi:[1,0]
	v_cmp_lt_i32_e32 vcc, s28, v28
	s_or_b64 s[16:17], vcc, s[16:17]
	s_waitcnt vmcnt(2)
	v_pk_mul_f32 v[24:25], v[74:75], v[24:25]
	v_pk_mul_f32 v[26:27], v[76:77], v[26:27]
	s_waitcnt vmcnt(1)
	v_pk_add_f32 v[76:77], v[78:79], 1.0 op_sel_hi:[1,0]
	v_pk_add_f32 v[74:75], v[80:81], 1.0 op_sel_hi:[1,0]
	s_waitcnt vmcnt(0)
	v_pk_fma_f32 v[24:25], v[76:77], v[24:25], v[82:83]
	v_pk_fma_f32 v[26:27], v[74:75], v[26:27], v[84:85]
	v_cvt_pk_bf16_f32 v24, v24, v25
	v_lshl_add_u64 v[74:75], v[62:63], 0, v[48:49]
	v_cvt_pk_bf16_f32 v25, v26, v27
	v_mov_b32_e32 v122, v24
	v_mov_b32_e32 v123, v25
	global_load_dwordx4 v[24:27], v[32:33], off offset:2048
	v_lshl_add_u64 v[78:79], v[60:61], 0, v[48:49]
	global_load_dwordx4 v[74:77], v[74:75], off
	s_waitcnt vmcnt(1)
	v_pk_mul_f32 v[20:21], v[24:25], v[20:21]
	global_load_dwordx4 v[78:81], v[78:79], off
	v_pk_mul_f32 v[22:23], v[26:27], v[22:23]
	s_waitcnt vmcnt(1)
	v_pk_add_f32 v[26:27], v[74:75], 1.0 op_sel_hi:[1,0]
	v_pk_add_f32 v[24:25], v[76:77], 1.0 op_sel_hi:[1,0]
	v_lshl_add_u64 v[74:75], v[60:61], 0, v[50:51]
	s_waitcnt vmcnt(0)
	v_pk_fma_f32 v[20:21], v[26:27], v[20:21], v[78:79]
	v_pk_fma_f32 v[22:23], v[24:25], v[22:23], v[80:81]
	v_cvt_pk_bf16_f32 v20, v20, v21
	v_lshl_add_u64 v[24:25], v[62:63], 0, v[50:51]
	v_cvt_pk_bf16_f32 v21, v22, v23
	v_mov_b32_e32 v124, v20
	v_mov_b32_e32 v125, v21
	global_load_dwordx4 v[20:23], v[32:33], off offset:3072
	s_waitcnt vmcnt(0)
	v_pk_mul_f32 v[16:17], v[16:17], v[20:21]
	global_load_dwordx4 v[24:27], v[24:25], off
	v_pk_mul_f32 v[18:19], v[18:19], v[22:23]
	global_load_dwordx4 v[74:77], v[74:75], off
	s_waitcnt vmcnt(1)
	v_pk_add_f32 v[22:23], v[24:25], 1.0 op_sel_hi:[1,0]
	v_pk_add_f32 v[20:21], v[26:27], 1.0 op_sel_hi:[1,0]
	s_waitcnt vmcnt(0)
	v_pk_fma_f32 v[16:17], v[16:17], v[22:23], v[74:75]
	v_pk_fma_f32 v[18:19], v[18:19], v[20:21], v[76:77]
	v_cvt_pk_bf16_f32 v16, v16, v17
	v_lshl_add_u64 v[20:21], v[62:63], 0, v[52:53]
	v_cvt_pk_bf16_f32 v17, v18, v19
	v_mov_b32_e32 v126, v16
	v_mov_b32_e32 v127, v17
	global_load_dwordx4 v[16:19], v[34:35], off
	v_lshl_add_u64 v[24:25], v[60:61], 0, v[52:53]
	global_load_dwordx4 v[20:23], v[20:21], off
	s_waitcnt vmcnt(1)
	v_pk_mul_f32 v[12:13], v[12:13], v[16:17]
	global_load_dwordx4 v[24:27], v[24:25], off
	v_pk_mul_f32 v[14:15], v[14:15], v[18:19]
	s_waitcnt vmcnt(1)
	v_pk_add_f32 v[18:19], v[20:21], 1.0 op_sel_hi:[1,0]
	v_pk_add_f32 v[16:17], v[22:23], 1.0 op_sel_hi:[1,0]
	v_lshl_add_u64 v[20:21], v[60:61], 0, v[54:55]
	s_waitcnt vmcnt(0)
	v_pk_fma_f32 v[12:13], v[12:13], v[18:19], v[24:25]
	v_pk_fma_f32 v[14:15], v[14:15], v[16:17], v[26:27]
	v_cvt_pk_bf16_f32 v12, v12, v13
	v_lshl_add_u64 v[16:17], v[62:63], 0, v[54:55]
	v_cvt_pk_bf16_f32 v13, v14, v15
	v_mov_b32_e32 v128, v12
	v_mov_b32_e32 v129, v13
	global_load_dwordx4 v[12:15], v[36:37], off
	s_waitcnt vmcnt(0)
	v_pk_mul_f32 v[8:9], v[8:9], v[12:13]
	global_load_dwordx4 v[16:19], v[16:17], off
	v_pk_mul_f32 v[10:11], v[10:11], v[14:15]
	global_load_dwordx4 v[20:23], v[20:21], off
	s_waitcnt vmcnt(1)
	v_pk_add_f32 v[14:15], v[16:17], 1.0 op_sel_hi:[1,0]
	v_pk_add_f32 v[12:13], v[18:19], 1.0 op_sel_hi:[1,0]
	s_waitcnt vmcnt(0)
	v_pk_fma_f32 v[8:9], v[8:9], v[14:15], v[20:21]
	v_pk_fma_f32 v[10:11], v[10:11], v[12:13], v[22:23]
	v_cvt_pk_bf16_f32 v8, v8, v9
	v_lshl_add_u64 v[12:13], v[62:63], 0, v[56:57]
	v_cvt_pk_bf16_f32 v9, v10, v11
	v_mov_b32_e32 v130, v8
	v_mov_b32_e32 v131, v9
	global_load_dwordx4 v[8:11], v[38:39], off
	v_lshl_add_u64 v[16:17], v[60:61], 0, v[56:57]
	global_load_dwordx4 v[12:15], v[12:13], off
	s_waitcnt vmcnt(1)
	v_pk_mul_f32 v[4:5], v[4:5], v[8:9]
	global_load_dwordx4 v[16:19], v[16:17], off
	v_pk_mul_f32 v[6:7], v[6:7], v[10:11]
	s_waitcnt vmcnt(1)
	v_pk_add_f32 v[10:11], v[12:13], 1.0 op_sel_hi:[1,0]
	v_pk_add_f32 v[8:9], v[14:15], 1.0 op_sel_hi:[1,0]
	v_lshl_add_u64 v[12:13], v[60:61], 0, v[58:59]
	s_waitcnt vmcnt(0)
	v_pk_fma_f32 v[4:5], v[4:5], v[10:11], v[16:17]
	v_pk_fma_f32 v[6:7], v[6:7], v[8:9], v[18:19]
	v_cvt_pk_bf16_f32 v4, v4, v5
	v_lshl_add_u64 v[8:9], v[62:63], 0, v[58:59]
	v_cvt_pk_bf16_f32 v5, v6, v7
	v_mov_b32_e32 v132, v4
	v_mov_b32_e32 v133, v5
	global_load_dwordx4 v[4:7], v[40:41], off
	s_waitcnt vmcnt(0)
	v_pk_mul_f32 v[0:1], v[0:1], v[4:5]
	global_load_dwordx4 v[8:11], v[8:9], off
	v_pk_mul_f32 v[2:3], v[2:3], v[6:7]
	global_load_dwordx4 v[12:15], v[12:13], off
	s_waitcnt vmcnt(1)
	v_pk_add_f32 v[6:7], v[8:9], 1.0 op_sel_hi:[1,0]
	v_pk_add_f32 v[4:5], v[10:11], 1.0 op_sel_hi:[1,0]
	s_waitcnt vmcnt(0)
	v_pk_fma_f32 v[0:1], v[0:1], v[6:7], v[12:13]
	v_pk_fma_f32 v[2:3], v[2:3], v[4:5], v[14:15]
	v_cvt_pk_bf16_f32 v0, v0, v1
	s_nop 0
	v_cvt_pk_bf16_f32 v1, v2, v3
	global_store_dwordx2 v[64:65], v[120:121], off
	global_store_dwordx2 v[64:65], v[122:123], off offset:512
	global_store_dwordx2 v[64:65], v[124:125], off offset:1024
	global_store_dwordx2 v[64:65], v[126:127], off offset:1536
	global_store_dwordx2 v[64:65], v[128:129], off offset:2048
	global_store_dwordx2 v[64:65], v[130:131], off offset:2560
	global_store_dwordx2 v[64:65], v[132:133], off offset:3072
	global_store_dwordx2 v[64:65], v[0:1], off offset:3584
	s_andn2_b64 exec, exec, s[16:17]
	s_cbranch_execz .LBB0_368

.LBB0_632:
	s_or_b64 exec, exec, s[4:5]
	v_lshl_add_u64 v[0:1], v[0:1], 0, v[30:31]
	global_load_dwordx4 v[80:83], v[0:1], off
	global_load_dwordx4 v[24:27], v[0:1], off offset:1024
	global_load_dwordx4 v[20:23], v[0:1], off offset:2048
	global_load_dwordx4 v[16:19], v[0:1], off offset:3072
	v_add_co_u32_e64 v68, s[4:5], s20, v0
	v_lshrrev_b32_e32 v53, 10, v66
	s_nop 0
	v_addc_co_u32_e64 v69, s[4:5], 0, v1, s[4:5]
	global_load_dwordx4 v[12:15], v[68:69], off
	global_load_dwordx4 v[8:11], v[68:69], off offset:1024
	global_load_dwordx4 v[4:7], v[68:69], off offset:2048
	global_load_dwordx4 v[0:3], v[68:69], off offset:3072
	v_add_u32_e32 v53, 1, v53
	v_mov_b64_e32 v[66:67], s[26:27]
	v_cndmask_b32_e64 v53, v53, 0, vcc
	v_mad_u64_u32 v[66:67], s[0:1], v53, s22, v[66:67]
	v_lshl_add_u64 v[68:69], v[66:67], 0, s[14:15]
	global_load_dwordx4 v[84:87], v[32:33], off
	v_lshl_add_u64 v[98:99], v[68:69], 0, v[30:31]
	v_lshl_add_u64 v[96:97], v[66:67], 0, v[30:31]
	global_load_dwordx4 v[88:91], v[98:99], off
	global_load_dwordx4 v[92:95], v[96:97], off
	v_lshlrev_b64 v[70:71], 12, v[70:71]
	v_lshl_add_u64 v[70:71], v[48:49], 0, v[70:71]
	v_mov_b32_e32 v61, v31
	v_mov_b32_e32 v63, v31
	v_mov_b32_e32 v65, v31
	v_lshl_add_u64 v[28:29], v[28:29], 0, s[12:13]
	v_lshl_add_u64 v[50:51], v[50:51], 0, s[16:17]
	s_waitcnt vmcnt(10)
	v_mul_f32_e32 v53, v81, v81
	s_waitcnt vmcnt(9)
	v_mul_f32_e32 v55, v25, v25
	s_waitcnt vmcnt(8)
	v_mul_f32_e32 v57, v21, v21
	v_fmac_f32_e32 v53, v80, v80
	v_fmac_f32_e32 v55, v24, v24
	s_waitcnt vmcnt(7)
	v_mul_f32_e32 v59, v17, v17
	v_fmac_f32_e32 v57, v20, v20
	s_waitcnt vmcnt(6)
	v_mov_b32_e32 v100, v13
	s_waitcnt vmcnt(5)
	v_mov_b32_e32 v101, v9
	v_fmac_f32_e32 v53, v82, v82
	v_fmac_f32_e32 v55, v26, v26
	v_fmac_f32_e32 v59, v16, v16
	v_mov_b32_e32 v98, v12
	v_mov_b32_e32 v99, v8
	v_fmac_f32_e32 v57, v22, v22
	v_pk_mul_f32 v[100:101], v[100:101], v[100:101]
	v_fmac_f32_e32 v53, v83, v83
	v_fmac_f32_e32 v55, v27, v27
	v_mov_b32_e32 v102, v14
	v_mov_b32_e32 v103, v10
	s_waitcnt vmcnt(4)
	v_mov_b32_e32 v108, v5
	s_waitcnt vmcnt(3)
	v_mov_b32_e32 v109, v1
	v_fmac_f32_e32 v59, v18, v18
	v_fmac_f32_e32 v57, v23, v23
	v_pk_fma_f32 v[98:99], v[98:99], v[98:99], v[100:101]
	v_add_f32_e32 v53, v53, v55
	v_mov_b32_e32 v104, v15
	v_mov_b32_e32 v105, v11
	v_mov_b32_e32 v106, v4
	v_mov_b32_e32 v107, v0
	v_pk_mul_f32 v[108:109], v[108:109], v[108:109]
	v_fmac_f32_e32 v59, v19, v19
	v_pk_fma_f32 v[98:99], v[102:103], v[102:103], v[98:99]
	v_add_f32_e32 v53, v53, v57
	v_mov_b32_e32 v110, v6
	v_mov_b32_e32 v111, v2
	v_pk_fma_f32 v[100:101], v[106:107], v[106:107], v[108:109]
	v_pk_fma_f32 v[98:99], v[104:105], v[104:105], v[98:99]
	v_add_f32_e32 v53, v53, v59
	v_mov_b32_e32 v112, v7
	v_mov_b32_e32 v113, v3
	v_pk_fma_f32 v[100:101], v[110:111], v[110:111], v[100:101]
	v_add_f32_e32 v53, v53, v98
	v_pk_fma_f32 v[100:101], v[112:113], v[112:113], v[100:101]
	v_add_f32_e32 v53, v53, v99
	v_add_f32_e32 v53, v53, v100
	v_add_f32_e32 v53, v53, v101
	ds_bpermute_b32 v55, v73, v53
	s_waitcnt vmcnt(1)
	v_pk_add_f32 v[88:89], v[88:89], 1.0 op_sel_hi:[1,0]
	v_pk_add_f32 v[90:91], v[90:91], 1.0 op_sel_hi:[1,0]
	v_mov_b32_e32 v59, v31
	s_waitcnt lgkmcnt(0)
	v_add_f32_e32 v53, v53, v55
	ds_bpermute_b32 v55, v74, v53
	s_waitcnt lgkmcnt(0)
	v_add_f32_e32 v53, v53, v55
	ds_bpermute_b32 v55, v75, v53
	s_waitcnt lgkmcnt(0)
	v_add_f32_e32 v53, v53, v55
	ds_bpermute_b32 v55, v76, v53
	s_waitcnt lgkmcnt(0)
	v_add_f32_e32 v53, v53, v55
	ds_bpermute_b32 v55, v77, v53
	s_waitcnt lgkmcnt(0)
	v_add_f32_e32 v55, v53, v55
	ds_bpermute_b32 v57, v78, v55
	v_mov_b32_e32 v53, v31
	s_waitcnt lgkmcnt(0)
	v_add_f32_e32 v55, v55, v57
	v_fmamk_f32 v55, v55, 0x3a000000, v79
	v_mul_f32_e32 v57, 0x4b800000, v55
	v_cmp_gt_f32_e32 vcc, s23, v55
	s_nop 1
	v_cndmask_b32_e32 v55, v55, v57, vcc
	v_rsq_f32_e32 v55, v55
	s_nop 0
	v_mul_f32_e32 v57, 0x45800000, v55
	v_cndmask_b32_e32 v72, v55, v57, vcc
	v_pk_mul_f32 v[80:81], v[80:81], v[72:73] op_sel_hi:[1,0]
	v_pk_mul_f32 v[82:83], v[82:83], v[72:73] op_sel_hi:[1,0]
	v_pk_mul_f32 v[80:81], v[84:85], v[80:81]
	v_pk_mul_f32 v[82:83], v[86:87], v[82:83]
	s_waitcnt vmcnt(0)
	v_pk_fma_f32 v[80:81], v[88:89], v[80:81], v[92:93]
	v_pk_fma_f32 v[82:83], v[90:91], v[82:83], v[94:95]
	v_cvt_pk_bf16_f32 v80, v80, v81
	v_lshl_add_u64 v[92:93], v[68:69], 0, v[52:53]
	v_cvt_pk_bf16_f32 v81, v82, v83
	v_mov_b32_e32 v120, v80
	v_mov_b32_e32 v121, v81
	global_load_dwordx4 v[80:83], v[34:35], off
	s_nop 0
	global_load_dwordx4 v[84:87], v[92:93], off
	global_load_dwordx4 v[88:91], v[96:97], off offset:1024
	v_pk_mul_f32 v[26:27], v[26:27], v[72:73] op_sel_hi:[1,0]
	v_pk_mul_f32 v[24:25], v[24:25], v[72:73] op_sel_hi:[1,0]
	v_mov_b32_e32 v55, v31
	v_pk_mul_f32 v[22:23], v[22:23], v[72:73] op_sel_hi:[1,0]
	v_pk_mul_f32 v[20:21], v[20:21], v[72:73] op_sel_hi:[1,0]
	v_mov_b32_e32 v57, v31
	v_pk_mul_f32 v[18:19], v[18:19], v[72:73] op_sel_hi:[1,0]
	v_pk_mul_f32 v[16:17], v[16:17], v[72:73] op_sel_hi:[1,0]
	v_pk_mul_f32 v[14:15], v[14:15], v[72:73] op_sel_hi:[1,0]
	v_pk_mul_f32 v[12:13], v[12:13], v[72:73] op_sel_hi:[1,0]
	v_pk_mul_f32 v[10:11], v[10:11], v[72:73] op_sel_hi:[1,0]
	v_pk_mul_f32 v[8:9], v[8:9], v[72:73] op_sel_hi:[1,0]
	v_pk_mul_f32 v[6:7], v[6:7], v[72:73] op_sel_hi:[1,0]
	v_pk_mul_f32 v[4:5], v[4:5], v[72:73] op_sel_hi:[1,0]
	v_pk_mul_f32 v[2:3], v[2:3], v[72:73] op_sel_hi:[1,0]
	v_pk_mul_f32 v[0:1], v[0:1], v[72:73] op_sel_hi:[1,0]
	v_cmp_lt_i32_e32 vcc, s24, v28
	s_or_b64 s[18:19], vcc, s[18:19]
	s_waitcnt vmcnt(2)
	v_pk_mul_f32 v[24:25], v[80:81], v[24:25]
	v_pk_mul_f32 v[26:27], v[82:83], v[26:27]
	s_waitcnt vmcnt(1)
	v_pk_add_f32 v[82:83], v[84:85], 1.0 op_sel_hi:[1,0]
	v_pk_add_f32 v[80:81], v[86:87], 1.0 op_sel_hi:[1,0]
	s_waitcnt vmcnt(0)
	v_pk_fma_f32 v[24:25], v[82:83], v[24:25], v[88:89]
	v_pk_fma_f32 v[26:27], v[80:81], v[26:27], v[90:91]
	v_cvt_pk_bf16_f32 v24, v24, v25
	v_lshl_add_u64 v[88:89], v[68:69], 0, v[54:55]
	v_cvt_pk_bf16_f32 v25, v26, v27
	v_mov_b32_e32 v122, v24
	v_mov_b32_e32 v123, v25
	global_load_dwordx4 v[24:27], v[36:37], off
	s_nop 0
	global_load_dwordx4 v[80:83], v[88:89], off
	global_load_dwordx4 v[84:87], v[96:97], off offset:2048
	s_waitcnt vmcnt(2)
	v_pk_mul_f32 v[20:21], v[24:25], v[20:21]
	v_pk_mul_f32 v[22:23], v[26:27], v[22:23]
	s_waitcnt vmcnt(1)
	v_pk_add_f32 v[26:27], v[80:81], 1.0 op_sel_hi:[1,0]
	v_pk_add_f32 v[24:25], v[82:83], 1.0 op_sel_hi:[1,0]
	s_waitcnt vmcnt(0)
	v_pk_fma_f32 v[20:21], v[26:27], v[20:21], v[84:85]
	v_pk_fma_f32 v[22:23], v[24:25], v[22:23], v[86:87]
	v_cvt_pk_bf16_f32 v20, v20, v21
	v_lshl_add_u64 v[84:85], v[68:69], 0, v[56:57]
	v_cvt_pk_bf16_f32 v21, v22, v23
	v_mov_b32_e32 v124, v20
	v_mov_b32_e32 v125, v21
	global_load_dwordx4 v[20:23], v[38:39], off
	s_nop 0
	global_load_dwordx4 v[24:27], v[84:85], off
	global_load_dwordx4 v[80:83], v[96:97], off offset:3072
	s_waitcnt vmcnt(2)
	v_pk_mul_f32 v[16:17], v[16:17], v[20:21]
	v_pk_mul_f32 v[18:19], v[18:19], v[22:23]
	s_waitcnt vmcnt(1)
	v_pk_add_f32 v[22:23], v[24:25], 1.0 op_sel_hi:[1,0]
	v_pk_add_f32 v[20:21], v[26:27], 1.0 op_sel_hi:[1,0]
	s_waitcnt vmcnt(0)
	v_pk_fma_f32 v[16:17], v[16:17], v[22:23], v[80:81]
	v_pk_fma_f32 v[18:19], v[18:19], v[20:21], v[82:83]
	v_cvt_pk_bf16_f32 v16, v16, v17
	v_lshl_add_u64 v[20:21], v[68:69], 0, v[58:59]
	v_cvt_pk_bf16_f32 v17, v18, v19
	v_mov_b32_e32 v126, v16
	v_mov_b32_e32 v127, v17
	global_load_dwordx4 v[16:19], v[40:41], off
	v_lshl_add_u64 v[24:25], v[66:67], 0, v[58:59]
	global_load_dwordx4 v[20:23], v[20:21], off
	s_waitcnt vmcnt(1)
	v_pk_mul_f32 v[12:13], v[12:13], v[16:17]
	global_load_dwordx4 v[24:27], v[24:25], off
	v_pk_mul_f32 v[14:15], v[14:15], v[18:19]
	s_waitcnt vmcnt(1)
	v_pk_add_f32 v[18:19], v[20:21], 1.0 op_sel_hi:[1,0]
	v_pk_add_f32 v[16:17], v[22:23], 1.0 op_sel_hi:[1,0]
	v_lshl_add_u64 v[20:21], v[66:67], 0, v[60:61]
	s_waitcnt vmcnt(0)
	v_pk_fma_f32 v[12:13], v[12:13], v[18:19], v[24:25]
	v_pk_fma_f32 v[14:15], v[14:15], v[16:17], v[26:27]
	v_cvt_pk_bf16_f32 v12, v12, v13
	v_lshl_add_u64 v[16:17], v[68:69], 0, v[60:61]
	v_cvt_pk_bf16_f32 v13, v14, v15
	v_mov_b32_e32 v128, v12
	v_mov_b32_e32 v129, v13
	global_load_dwordx4 v[12:15], v[42:43], off
	s_waitcnt vmcnt(0)
	v_pk_mul_f32 v[8:9], v[8:9], v[12:13]
	global_load_dwordx4 v[16:19], v[16:17], off
	v_pk_mul_f32 v[10:11], v[10:11], v[14:15]
	global_load_dwordx4 v[20:23], v[20:21], off
	s_waitcnt vmcnt(1)
	v_pk_add_f32 v[14:15], v[16:17], 1.0 op_sel_hi:[1,0]
	v_pk_add_f32 v[12:13], v[18:19], 1.0 op_sel_hi:[1,0]
	s_waitcnt vmcnt(0)
	v_pk_fma_f32 v[8:9], v[8:9], v[14:15], v[20:21]
	v_pk_fma_f32 v[10:11], v[10:11], v[12:13], v[22:23]
	v_cvt_pk_bf16_f32 v8, v8, v9
	v_lshl_add_u64 v[12:13], v[68:69], 0, v[62:63]
	v_cvt_pk_bf16_f32 v9, v10, v11
	v_mov_b32_e32 v130, v8
	v_mov_b32_e32 v131, v9
	global_load_dwordx4 v[8:11], v[44:45], off
	v_lshl_add_u64 v[16:17], v[66:67], 0, v[62:63]
	global_load_dwordx4 v[12:15], v[12:13], off
	s_waitcnt vmcnt(1)
	v_pk_mul_f32 v[4:5], v[4:5], v[8:9]
	global_load_dwordx4 v[16:19], v[16:17], off
	v_pk_mul_f32 v[6:7], v[6:7], v[10:11]
	s_waitcnt vmcnt(1)
	v_pk_add_f32 v[10:11], v[12:13], 1.0 op_sel_hi:[1,0]
	v_pk_add_f32 v[8:9], v[14:15], 1.0 op_sel_hi:[1,0]
	v_lshl_add_u64 v[12:13], v[66:67], 0, v[64:65]
	s_waitcnt vmcnt(0)
	v_pk_fma_f32 v[4:5], v[4:5], v[10:11], v[16:17]
	v_pk_fma_f32 v[6:7], v[6:7], v[8:9], v[18:19]
	v_cvt_pk_bf16_f32 v4, v4, v5
	v_lshl_add_u64 v[8:9], v[68:69], 0, v[64:65]
	v_cvt_pk_bf16_f32 v5, v6, v7
	v_mov_b32_e32 v132, v4
	v_mov_b32_e32 v133, v5
	global_load_dwordx4 v[4:7], v[46:47], off
	s_waitcnt vmcnt(0)
	v_pk_mul_f32 v[0:1], v[0:1], v[4:5]
	global_load_dwordx4 v[8:11], v[8:9], off
	v_pk_mul_f32 v[2:3], v[2:3], v[6:7]
	global_load_dwordx4 v[12:15], v[12:13], off
	s_waitcnt vmcnt(1)
	v_pk_add_f32 v[6:7], v[8:9], 1.0 op_sel_hi:[1,0]
	v_pk_add_f32 v[4:5], v[10:11], 1.0 op_sel_hi:[1,0]
	s_waitcnt vmcnt(0)
	v_pk_fma_f32 v[0:1], v[0:1], v[6:7], v[12:13]
	v_pk_fma_f32 v[2:3], v[2:3], v[4:5], v[14:15]
	v_cvt_pk_bf16_f32 v0, v0, v1
	s_nop 0
	v_cvt_pk_bf16_f32 v1, v2, v3
	global_store_dwordx2 v[70:71], v[120:121], off
	global_store_dwordx2 v[70:71], v[122:123], off offset:512
	global_store_dwordx2 v[70:71], v[124:125], off offset:1024
	global_store_dwordx2 v[70:71], v[126:127], off offset:1536
	global_store_dwordx2 v[70:71], v[128:129], off offset:2048
	global_store_dwordx2 v[70:71], v[130:131], off offset:2560
	global_store_dwordx2 v[70:71], v[132:133], off offset:3072
	global_store_dwordx2 v[70:71], v[0:1], off offset:3584
	s_andn2_b64 exec, exec, s[18:19]
	s_cbranch_execz .LBB0_637

.LBB0_1071:
	s_or_b64 exec, exec, s[4:5]
	v_lshl_add_u64 v[0:1], v[0:1], 0, v[30:31]
	global_load_dwordx4 v[80:83], v[0:1], off
	global_load_dwordx4 v[24:27], v[0:1], off offset:1024
	global_load_dwordx4 v[20:23], v[0:1], off offset:2048
	global_load_dwordx4 v[16:19], v[0:1], off offset:3072
	v_add_co_u32_e64 v68, s[4:5], s3, v0
	v_lshrrev_b32_e32 v53, 10, v66
	s_nop 0
	v_addc_co_u32_e64 v69, s[4:5], 0, v1, s[4:5]
	global_load_dwordx4 v[12:15], v[68:69], off
	global_load_dwordx4 v[8:11], v[68:69], off offset:1024
	global_load_dwordx4 v[4:7], v[68:69], off offset:2048
	global_load_dwordx4 v[0:3], v[68:69], off offset:3072
	v_add_u32_e32 v53, 1, v53
	v_mov_b64_e32 v[66:67], s[28:29]
	v_cndmask_b32_e64 v53, v53, 0, vcc
	v_mad_u64_u32 v[68:69], s[0:1], v53, s23, v[66:67]
	v_lshl_add_u64 v[66:67], v[68:69], 0, s[18:19]
	v_lshl_add_u64 v[68:69], v[68:69], 0, s[20:21]
	global_load_dwordx4 v[84:87], v[32:33], off
	v_lshl_add_u64 v[96:97], v[68:69], 0, v[30:31]
	v_lshl_add_u64 v[98:99], v[66:67], 0, v[30:31]
	global_load_dwordx4 v[88:91], v[96:97], off
	global_load_dwordx4 v[92:95], v[98:99], off
	v_lshlrev_b64 v[70:71], 12, v[70:71]
	v_lshl_add_u64 v[70:71], v[48:49], 0, v[70:71]
	v_mov_b32_e32 v61, v31
	v_mov_b32_e32 v63, v31
	v_mov_b32_e32 v65, v31
	v_lshl_add_u64 v[28:29], v[28:29], 0, s[12:13]
	v_lshl_add_u64 v[50:51], v[50:51], 0, s[14:15]
	s_waitcnt vmcnt(10)
	v_mul_f32_e32 v53, v81, v81
	s_waitcnt vmcnt(9)
	v_mul_f32_e32 v55, v25, v25
	s_waitcnt vmcnt(8)
	v_mul_f32_e32 v57, v21, v21
	v_fmac_f32_e32 v53, v80, v80
	v_fmac_f32_e32 v55, v24, v24
	s_waitcnt vmcnt(7)
	v_mul_f32_e32 v59, v17, v17
	v_fmac_f32_e32 v57, v20, v20
	s_waitcnt vmcnt(6)
	v_mov_b32_e32 v98, v13
	s_waitcnt vmcnt(5)
	v_mov_b32_e32 v99, v9
	v_fmac_f32_e32 v53, v82, v82
	v_fmac_f32_e32 v55, v26, v26
	v_fmac_f32_e32 v59, v16, v16
	v_mov_b32_e32 v96, v12
	v_mov_b32_e32 v97, v8
	v_fmac_f32_e32 v57, v22, v22
	v_pk_mul_f32 v[98:99], v[98:99], v[98:99]
	v_fmac_f32_e32 v53, v83, v83
	v_fmac_f32_e32 v55, v27, v27
	v_mov_b32_e32 v100, v14
	v_mov_b32_e32 v101, v10
	s_waitcnt vmcnt(4)
	v_mov_b32_e32 v106, v5
	s_waitcnt vmcnt(3)
	v_mov_b32_e32 v107, v1
	v_fmac_f32_e32 v59, v18, v18
	v_fmac_f32_e32 v57, v23, v23
	v_pk_fma_f32 v[96:97], v[96:97], v[96:97], v[98:99]
	v_add_f32_e32 v53, v53, v55
	v_mov_b32_e32 v102, v15
	v_mov_b32_e32 v103, v11
	v_mov_b32_e32 v104, v4
	v_mov_b32_e32 v105, v0
	v_pk_mul_f32 v[106:107], v[106:107], v[106:107]
	v_fmac_f32_e32 v59, v19, v19
	v_pk_fma_f32 v[96:97], v[100:101], v[100:101], v[96:97]
	v_add_f32_e32 v53, v53, v57
	v_mov_b32_e32 v108, v6
	v_mov_b32_e32 v109, v2
	v_pk_fma_f32 v[98:99], v[104:105], v[104:105], v[106:107]
	v_pk_fma_f32 v[96:97], v[102:103], v[102:103], v[96:97]
	v_add_f32_e32 v53, v53, v59
	v_mov_b32_e32 v110, v7
	v_mov_b32_e32 v111, v3
	v_pk_fma_f32 v[98:99], v[108:109], v[108:109], v[98:99]
	v_add_f32_e32 v53, v53, v96
	v_pk_fma_f32 v[98:99], v[110:111], v[110:111], v[98:99]
	v_add_f32_e32 v53, v53, v97
	v_add_f32_e32 v53, v53, v98
	v_add_f32_e32 v53, v53, v99
	ds_bpermute_b32 v55, v73, v53
	s_waitcnt vmcnt(1)
	v_pk_add_f32 v[88:89], v[88:89], 1.0 op_sel_hi:[1,0]
	v_pk_add_f32 v[90:91], v[90:91], 1.0 op_sel_hi:[1,0]
	v_mov_b32_e32 v59, v31
	s_waitcnt lgkmcnt(0)
	v_add_f32_e32 v53, v53, v55
	ds_bpermute_b32 v55, v74, v53
	s_waitcnt lgkmcnt(0)
	v_add_f32_e32 v53, v53, v55
	ds_bpermute_b32 v55, v75, v53
	s_waitcnt lgkmcnt(0)
	v_add_f32_e32 v53, v53, v55
	ds_bpermute_b32 v55, v76, v53
	s_waitcnt lgkmcnt(0)
	v_add_f32_e32 v53, v53, v55
	ds_bpermute_b32 v55, v77, v53
	s_waitcnt lgkmcnt(0)
	v_add_f32_e32 v55, v53, v55
	ds_bpermute_b32 v57, v78, v55
	v_mov_b32_e32 v53, v31
	s_waitcnt lgkmcnt(0)
	v_add_f32_e32 v55, v55, v57
	v_fmamk_f32 v55, v55, 0x3a000000, v79
	v_mul_f32_e32 v57, 0x4b800000, v55
	v_cmp_gt_f32_e32 vcc, s24, v55
	s_nop 1
	v_cndmask_b32_e32 v55, v55, v57, vcc
	v_rsq_f32_e32 v55, v55
	s_nop 0
	v_mul_f32_e32 v57, 0x45800000, v55
	v_cndmask_b32_e32 v72, v55, v57, vcc
	v_pk_mul_f32 v[80:81], v[80:81], v[72:73] op_sel_hi:[1,0]
	v_pk_mul_f32 v[82:83], v[82:83], v[72:73] op_sel_hi:[1,0]
	v_pk_mul_f32 v[80:81], v[84:85], v[80:81]
	v_pk_mul_f32 v[82:83], v[86:87], v[82:83]
	s_waitcnt vmcnt(0)
	v_pk_fma_f32 v[80:81], v[88:89], v[80:81], v[92:93]
	v_pk_fma_f32 v[82:83], v[90:91], v[82:83], v[94:95]
	v_cvt_pk_bf16_f32 v80, v80, v81
	v_lshl_add_u64 v[84:85], v[68:69], 0, v[52:53]
	v_cvt_pk_bf16_f32 v81, v82, v83
	v_mov_b32_e32 v120, v80
	v_mov_b32_e32 v121, v81
	global_load_dwordx4 v[80:83], v[34:35], off
	v_lshl_add_u64 v[88:89], v[66:67], 0, v[52:53]
	global_load_dwordx4 v[84:87], v[84:85], off
	v_pk_mul_f32 v[26:27], v[26:27], v[72:73] op_sel_hi:[1,0]
	global_load_dwordx4 v[88:91], v[88:89], off
	v_pk_mul_f32 v[24:25], v[24:25], v[72:73] op_sel_hi:[1,0]
	v_mov_b32_e32 v55, v31
	v_pk_mul_f32 v[22:23], v[22:23], v[72:73] op_sel_hi:[1,0]
	v_pk_mul_f32 v[20:21], v[20:21], v[72:73] op_sel_hi:[1,0]
	v_mov_b32_e32 v57, v31
	v_pk_mul_f32 v[18:19], v[18:19], v[72:73] op_sel_hi:[1,0]
	v_pk_mul_f32 v[16:17], v[16:17], v[72:73] op_sel_hi:[1,0]
	v_pk_mul_f32 v[14:15], v[14:15], v[72:73] op_sel_hi:[1,0]
	v_pk_mul_f32 v[12:13], v[12:13], v[72:73] op_sel_hi:[1,0]
	v_pk_mul_f32 v[10:11], v[10:11], v[72:73] op_sel_hi:[1,0]
	v_pk_mul_f32 v[8:9], v[8:9], v[72:73] op_sel_hi:[1,0]
	v_pk_mul_f32 v[6:7], v[6:7], v[72:73] op_sel_hi:[1,0]
	v_pk_mul_f32 v[4:5], v[4:5], v[72:73] op_sel_hi:[1,0]
	v_pk_mul_f32 v[2:3], v[2:3], v[72:73] op_sel_hi:[1,0]
	v_pk_mul_f32 v[0:1], v[0:1], v[72:73] op_sel_hi:[1,0]
	v_cmp_lt_i32_e32 vcc, s25, v28
	s_or_b64 s[16:17], vcc, s[16:17]
	s_waitcnt vmcnt(2)
	v_pk_mul_f32 v[24:25], v[80:81], v[24:25]
	v_pk_mul_f32 v[26:27], v[82:83], v[26:27]
	s_waitcnt vmcnt(1)
	v_pk_add_f32 v[82:83], v[84:85], 1.0 op_sel_hi:[1,0]
	v_pk_add_f32 v[80:81], v[86:87], 1.0 op_sel_hi:[1,0]
	s_waitcnt vmcnt(0)
	v_pk_fma_f32 v[24:25], v[82:83], v[24:25], v[88:89]
	v_pk_fma_f32 v[26:27], v[80:81], v[26:27], v[90:91]
	v_cvt_pk_bf16_f32 v24, v24, v25
	v_lshl_add_u64 v[80:81], v[68:69], 0, v[54:55]
	v_cvt_pk_bf16_f32 v25, v26, v27
	v_mov_b32_e32 v122, v24
	v_mov_b32_e32 v123, v25
	global_load_dwordx4 v[24:27], v[36:37], off
	v_lshl_add_u64 v[84:85], v[66:67], 0, v[54:55]
	global_load_dwordx4 v[80:83], v[80:81], off
	s_waitcnt vmcnt(1)
	v_pk_mul_f32 v[20:21], v[24:25], v[20:21]
	global_load_dwordx4 v[84:87], v[84:85], off
	v_pk_mul_f32 v[22:23], v[26:27], v[22:23]
	s_waitcnt vmcnt(1)
	v_pk_add_f32 v[26:27], v[80:81], 1.0 op_sel_hi:[1,0]
	v_pk_add_f32 v[24:25], v[82:83], 1.0 op_sel_hi:[1,0]
	v_lshl_add_u64 v[80:81], v[66:67], 0, v[56:57]
	s_waitcnt vmcnt(0)
	v_pk_fma_f32 v[20:21], v[26:27], v[20:21], v[84:85]
	v_pk_fma_f32 v[22:23], v[24:25], v[22:23], v[86:87]
	v_cvt_pk_bf16_f32 v20, v20, v21
	v_lshl_add_u64 v[24:25], v[68:69], 0, v[56:57]
	v_cvt_pk_bf16_f32 v21, v22, v23
	v_mov_b32_e32 v124, v20
	v_mov_b32_e32 v125, v21
	global_load_dwordx4 v[20:23], v[38:39], off
	s_waitcnt vmcnt(0)
	v_pk_mul_f32 v[16:17], v[16:17], v[20:21]
	global_load_dwordx4 v[24:27], v[24:25], off
	v_pk_mul_f32 v[18:19], v[18:19], v[22:23]
	global_load_dwordx4 v[80:83], v[80:81], off
	s_waitcnt vmcnt(1)
	v_pk_add_f32 v[22:23], v[24:25], 1.0 op_sel_hi:[1,0]
	v_pk_add_f32 v[20:21], v[26:27], 1.0 op_sel_hi:[1,0]
	s_waitcnt vmcnt(0)
	v_pk_fma_f32 v[16:17], v[16:17], v[22:23], v[80:81]
	v_pk_fma_f32 v[18:19], v[18:19], v[20:21], v[82:83]
	v_cvt_pk_bf16_f32 v16, v16, v17
	v_lshl_add_u64 v[20:21], v[68:69], 0, v[58:59]
	v_cvt_pk_bf16_f32 v17, v18, v19
	v_mov_b32_e32 v126, v16
	v_mov_b32_e32 v127, v17
	global_load_dwordx4 v[16:19], v[40:41], off
	v_lshl_add_u64 v[24:25], v[66:67], 0, v[58:59]
	global_load_dwordx4 v[20:23], v[20:21], off
	s_waitcnt vmcnt(1)
	v_pk_mul_f32 v[12:13], v[12:13], v[16:17]
	global_load_dwordx4 v[24:27], v[24:25], off
	v_pk_mul_f32 v[14:15], v[14:15], v[18:19]
	s_waitcnt vmcnt(1)
	v_pk_add_f32 v[18:19], v[20:21], 1.0 op_sel_hi:[1,0]
	v_pk_add_f32 v[16:17], v[22:23], 1.0 op_sel_hi:[1,0]
	v_lshl_add_u64 v[20:21], v[66:67], 0, v[60:61]
	s_waitcnt vmcnt(0)
	v_pk_fma_f32 v[12:13], v[12:13], v[18:19], v[24:25]
	v_pk_fma_f32 v[14:15], v[14:15], v[16:17], v[26:27]
	v_cvt_pk_bf16_f32 v12, v12, v13
	v_lshl_add_u64 v[16:17], v[68:69], 0, v[60:61]
	v_cvt_pk_bf16_f32 v13, v14, v15
	v_mov_b32_e32 v128, v12
	v_mov_b32_e32 v129, v13
	global_load_dwordx4 v[12:15], v[42:43], off
	s_waitcnt vmcnt(0)
	v_pk_mul_f32 v[8:9], v[8:9], v[12:13]
	global_load_dwordx4 v[16:19], v[16:17], off
	v_pk_mul_f32 v[10:11], v[10:11], v[14:15]
	global_load_dwordx4 v[20:23], v[20:21], off
	s_waitcnt vmcnt(1)
	v_pk_add_f32 v[14:15], v[16:17], 1.0 op_sel_hi:[1,0]
	v_pk_add_f32 v[12:13], v[18:19], 1.0 op_sel_hi:[1,0]
	s_waitcnt vmcnt(0)
	v_pk_fma_f32 v[8:9], v[8:9], v[14:15], v[20:21]
	v_pk_fma_f32 v[10:11], v[10:11], v[12:13], v[22:23]
	v_cvt_pk_bf16_f32 v8, v8, v9
	v_lshl_add_u64 v[12:13], v[68:69], 0, v[62:63]
	v_cvt_pk_bf16_f32 v9, v10, v11
	v_mov_b32_e32 v130, v8
	v_mov_b32_e32 v131, v9
	global_load_dwordx4 v[8:11], v[44:45], off
	v_lshl_add_u64 v[16:17], v[66:67], 0, v[62:63]
	global_load_dwordx4 v[12:15], v[12:13], off
	s_waitcnt vmcnt(1)
	v_pk_mul_f32 v[4:5], v[4:5], v[8:9]
	global_load_dwordx4 v[16:19], v[16:17], off
	v_pk_mul_f32 v[6:7], v[6:7], v[10:11]
	s_waitcnt vmcnt(1)
	v_pk_add_f32 v[10:11], v[12:13], 1.0 op_sel_hi:[1,0]
	v_pk_add_f32 v[8:9], v[14:15], 1.0 op_sel_hi:[1,0]
	v_lshl_add_u64 v[12:13], v[66:67], 0, v[64:65]
	s_waitcnt vmcnt(0)
	v_pk_fma_f32 v[4:5], v[4:5], v[10:11], v[16:17]
	v_pk_fma_f32 v[6:7], v[6:7], v[8:9], v[18:19]
	v_cvt_pk_bf16_f32 v4, v4, v5
	v_lshl_add_u64 v[8:9], v[68:69], 0, v[64:65]
	v_cvt_pk_bf16_f32 v5, v6, v7
	v_mov_b32_e32 v132, v4
	v_mov_b32_e32 v133, v5
	global_load_dwordx4 v[4:7], v[46:47], off
	s_waitcnt vmcnt(0)
	v_pk_mul_f32 v[0:1], v[0:1], v[4:5]
	global_load_dwordx4 v[8:11], v[8:9], off
	v_pk_mul_f32 v[2:3], v[2:3], v[6:7]
	global_load_dwordx4 v[12:15], v[12:13], off
	s_waitcnt vmcnt(1)
	v_pk_add_f32 v[6:7], v[8:9], 1.0 op_sel_hi:[1,0]
	v_pk_add_f32 v[4:5], v[10:11], 1.0 op_sel_hi:[1,0]
	s_waitcnt vmcnt(0)
	v_pk_fma_f32 v[0:1], v[0:1], v[6:7], v[12:13]
	v_pk_fma_f32 v[2:3], v[2:3], v[4:5], v[14:15]
	v_cvt_pk_bf16_f32 v0, v0, v1
	s_nop 0
	v_cvt_pk_bf16_f32 v1, v2, v3
	global_store_dwordx2 v[70:71], v[120:121], off
	global_store_dwordx2 v[70:71], v[122:123], off offset:512
	global_store_dwordx2 v[70:71], v[124:125], off offset:1024
	global_store_dwordx2 v[70:71], v[126:127], off offset:1536
	global_store_dwordx2 v[70:71], v[128:129], off offset:2048
	global_store_dwordx2 v[70:71], v[130:131], off offset:2560
	global_store_dwordx2 v[70:71], v[132:133], off offset:3072
	global_store_dwordx2 v[70:71], v[0:1], off offset:3584
	s_andn2_b64 exec, exec, s[16:17]
	s_cbranch_execz .LBB0_1076
